# P0: first row's x prefetch issued before the weight-transpose loop (its latency overlaps the setup)
# baseline (speedup 1.0000x reference)
.LBB0_13:
	s_or_b64 exec, exec, s[0:1]
	s_lshl_b32 s0, s14, 3
	v_lshrrev_b32_e32 v7, 6, v0
	v_writelane_b32 v254, s0, 37
	v_or_b32_e32 v42, s0, v7
	s_movk_i32 s0, 0x1000
	v_and_b32_e32 v148, 63, v0
	v_add_u32_e32 v134, 0xffffc000, v42
	v_cmp_gt_i32_e32 vcc, 0x4000, v42
	v_mov_b32_e32 v136, s54
	v_mov_b32_e32 v137, s52
	v_mov_b32_e32 v140, s55
	v_mov_b32_e32 v141, s53
	v_mov_b32_e32 v135, 0
	v_cndmask_b32_e32 v134, v134, v42, vcc
	v_cndmask_b32_e32 v139, v140, v141, vcc
	v_cndmask_b32_e32 v138, v136, v137, vcc
	v_lshlrev_b64 v[134:135], 12, v[134:135]
	v_lshl_add_u64 v[134:135], v[138:139], 0, v[134:135]
	v_lshlrev_b32_e32 v142, 4, v148
	v_mov_b32_e32 v143, 0
	v_lshl_add_u64 v[134:135], v[134:135], 0, v[142:143]
	global_load_dwordx4 v[116:119], v[134:135], off
	global_load_dwordx4 v[120:123], v[134:135], off offset:1024
	global_load_dwordx4 v[124:127], v[134:135], off offset:3072
	global_load_dwordx4 v[128:131], v[134:135], off offset:2048
	s_lshl_b32 s33, s90, 3
	v_cmp_gt_i32_e32 vcc, s0, v42
	s_and_saveexec_b64 s[0:1], vcc
	s_cbranch_execz .LBB0_16
	s_movk_i32 s2, 0x2100
	v_mad_u32_u24 v8, v7, s2, 0
	v_lshrrev_b32_e32 v1, 3, v148
	v_lshlrev_b32_e32 v4, 4, v6
	v_add_u32_e32 v9, v8, v4
	v_mul_u32_u24_e32 v10, 0x84, v1
	v_mul_u32_u24_e32 v6, 0x420, v6
	v_mov_b32_e32 v5, 0
	v_lshlrev_b32_e32 v11, 2, v1
	v_lshl_add_u64 v[2:3], s[74:75], 0, v[4:5]
	s_mov_b64 s[2:3], 0x8000
	v_add3_u32 v6, v8, v6, v11
	v_lshlrev_b32_e32 v7, 5, v7
	v_add_u32_e32 v8, v9, v10
	v_lshl_add_u64 v[2:3], v[2:3], 0, s[2:3]
	v_lshl_add_u64 v[4:5], s[66:67], 0, v[4:5]
	v_lshl_or_b32 v7, s14, 8, v7
	s_lshl_b32 s4, s33, 5
	s_mov_b64 s[2:3], 0
	s_movk_i32 s5, 0xc0
	s_mov_b32 s6, 0x8020
	v_add_u32_e32 v9, 0x420, v8
	v_add_u32_e32 v10, 0x428, v8
	v_add_u32_e32 v11, 0x840, v8
	v_add_u32_e32 v12, 0x848, v8
	v_add_u32_e32 v13, 0xc60, v8
	v_add_u32_e32 v14, 0xc68, v8
	v_add_u32_e32 v15, 0x1080, v8
	v_add_u32_e32 v16, 0x1088, v8
	v_add_u32_e32 v17, 0x14a0, v8
	v_add_u32_e32 v18, 0x14a8, v8
	v_add_u32_e32 v19, 0x18c0, v8
	v_add_u32_e32 v20, 0x18c8, v8
	v_add_u32_e32 v21, 0x1ce0, v8
	v_add_u32_e32 v22, 0x1ce8, v8
	s_movk_i32 s7, 0xfff
	v_mov_b32_e32 v23, v42

.LBB0_23:
	s_or_b64 exec, exec, s[0:1]
	s_movk_i32 s24, 0x4200
	v_cmp_gt_i32_e32 vcc, s24, v42
	v_mbcnt_lo_u32_b32 v185, -1, 0
	s_waitcnt lgkmcnt(0)
	s_barrier
	s_and_saveexec_b64 s[0:1], vcc
	s_cbranch_execz .LBB0_31
	v_readlane_b32 s76, v254, 5
	v_readlane_b32 s77, v254, 6
	v_readlane_b32 s78, v254, 7
	v_readlane_b32 s79, v254, 8
	v_and_b32_e32 v112, 3, v148
	v_lshlrev_b32_e32 v112, 2, v112
	s_nop 4
	global_load_dword v110, v112, s[76:77]
	global_load_dword v111, v112, s[78:79]
	s_mov_b64 s[18:19], 2
	s_mov_b64 s[20:21], 4
	s_mov_b64 s[22:23], 8
	s_mov_b64 s[68:69], 15
	v_lshlrev_b32_e32 v1, 4, v148
	global_load_dwordx4 v[2:5], v1, s[64:65]
	global_load_dwordx4 v[6:9], v1, s[64:65] offset:1024
	global_load_dwordx4 v[10:13], v1, s[64:65] offset:2048
	global_load_dwordx4 v[14:17], v1, s[64:65] offset:3072
	v_mbcnt_hi_u32_b32 v18, -1, v185
	v_and_b32_e32 v19, 64, v18
	v_add_u32_e32 v19, 64, v19
	v_xor_b32_e32 v20, 1, v18
	v_cmp_lt_i32_e32 vcc, v20, v19
	s_lshl_b32 s6, s90, 4
	v_ashrrev_i32_e32 v43, 31, v42
	v_cndmask_b32_e32 v20, v18, v20, vcc
	v_lshlrev_b32_e32 v66, 2, v20
	v_xor_b32_e32 v20, 2, v18
	v_cmp_lt_i32_e32 vcc, v20, v19
	s_ashr_i32 s7, s6, 31
	v_lshlrev_b64 v[50:51], 11, v[42:43]
	v_cndmask_b32_e32 v20, v18, v20, vcc
	v_lshlrev_b32_e32 v67, 2, v20
	v_xor_b32_e32 v20, 4, v18
	v_cmp_lt_i32_e32 vcc, v20, v19
	v_mov_b32_e32 v45, 0
	v_add_u32_e32 v1, s73, v1
	v_cndmask_b32_e32 v20, v18, v20, vcc
	v_lshlrev_b32_e32 v68, 2, v20
	v_xor_b32_e32 v20, 8, v18
	v_cmp_lt_i32_e32 vcc, v20, v19
	v_cmp_eq_u32_e64 s[2:3], 0, v148
	s_lshl_b64 s[8:9], s[6:7], 5
	v_cndmask_b32_e32 v20, v18, v20, vcc
	v_lshlrev_b32_e32 v69, 2, v20
	v_xor_b32_e32 v20, 16, v18
	v_cmp_lt_i32_e32 vcc, v20, v19
	s_lshl_b64 s[10:11], s[6:7], 11
	v_lshlrev_b64 v[52:53], 5, v[42:43]
	v_cndmask_b32_e32 v20, v18, v20, vcc
	v_lshlrev_b32_e32 v70, 2, v20
	v_xor_b32_e32 v20, 32, v18
	v_cmp_lt_i32_e32 vcc, v20, v19
	s_mov_b64 s[12:13], 0
	s_movk_i32 s25, 0x4000
	v_cndmask_b32_e32 v18, v18, v20, vcc
	v_lshlrev_b32_e32 v71, 2, v18
	v_add_u32_e32 v18, s33, v42
	v_ashrrev_i32_e32 v19, 31, v18
	v_lshlrev_b64 v[46:47], 5, v[18:19]
	v_lshlrev_b64 v[48:49], 11, v[18:19]
	v_lshlrev_b32_e32 v18, 3, v148
	v_or_b32_e32 v48, v48, v18
	v_or_b32_e32 v50, v50, v18
	v_mov_b32_e32 v72, s55
	v_mov_b32_e32 v73, s53
	v_lshlrev_b32_e32 v44, 4, v148
	v_mov_b32_e32 v74, 0x358637bd
	s_mov_b32 s28, 0x800000
	s_mov_b32 s29, 0x276e000
	s_mov_b32 s30, 0xbfb8aa3b
	s_mov_b32 s31, 0xb2a5705f
	s_mov_b32 s34, 0x42ce8ed0
	s_mov_b32 s35, 0xc2b17218
	s_mov_b32 s64, 0x7f800000
	s_mov_b32 s65, 0x3f2aaaab
	v_mov_b32_e32 v75, 0x3ecc95a3
	s_mov_b32 s66, 0x3f317218
	s_mov_b32 s67, 0x33800000
	s_movk_i32 s84, 0x41ff
	v_mov_b32_e32 v76, 0x7f800000
	s_waitcnt vmcnt(0)
	s_branch .LBB0_26
